# v071 plus dn_pre L2 warm-up: each thread touches one line of the next item's input rows late in the current item
# speedup vs baseline: 1.0100x; 1.0033x over previous
; __device__ __forceinline__ int ptid_(int wave) { int l_; asm volatile("v_mbcnt_lo_u32_b32 %0, -1, 0\n\tv_mbcnt_hi_u32_b32 %0, -1, %0" : "=v"(l_)); return (wave << 6) | l_; }
; __device__ void dn_pre_item(const Params& p, int L, int idx) {
;     ...
;   const int b = idx >> 8, h = (idx >> 6) & 3, n = idx & 63;
;   const long R0 = (long)b * TSEQ + n * 64;
;   int zoff = 0; asm volatile("" : "+v"(zoff));
;   unsigned char* sb = smem + zoff;
;   float* As = (float*)sb; float* gcs = As + 64 * 65; float* betas = gcs + 64; float* egc = betas + 64;
;   float* qs = (float*)(sb + 17408); float* ks = (float*)(sb + 51200); float* vs = (float*)(sb + 84992);
;   bfu* kb = (bfu*)(sb + 118784); bfu* qb = (bfu*)(sb + 136192);
;   float* Tf = (float*)(sb + 17408); bfu* Tb = (bfu*)(sb + 34048); float* Mt = (float*)(sb + 43264);
;   bfu* rhsT = (bfu*)(sb + 118784);
;   int tid = ptid_(p.tid); asm volatile("" : "+v"(tid)); const int wid = tid >> 6, lane = tid & 63;
;   const int c16 = lane & 15, q4 = lane >> 4;
;   __syncthreads();
;   float gv_pre = 0.f, be_pre = 0.f;
;   if (wid == 0) { gv_pre = misc[MF_BG + (R0 + lane) * 8 + 4 + h]; be_pre = misc[MF_BG + (R0 + lane) * 8 + h]; }
;   { const int c = tid & 127, rg = tid >> 7;
;     const int r0 = rg * 16;
;     const bool head0 = (n == 0) && (rg == 0);
;     bfu xr[3][19]; float cwv[3][4];
;     _Pragma("unroll") for (int mat = 0; mat < 3; ++mat) {
;       const int colp = mat * 512 + h * 128 + c;
;       const float* cw = p.dn_conv_w + (long)li * 4 * 1536 + colp;
;       _Pragma("unroll") for (int jw = 0; jw < 4; ++jw) cwv[mat][jw] = cw[jw * 1536];
;       _Pragma("unroll") for (int i = 0; i < 19; ++i) {
;         const long rr = R0 + r0 - 3 + i;
;         xr[mat][i] = pab[((i < 3 && head0) ? R0 : rr) * 3584 + colp];
;     ...
;   { const int i = tid >> 4, j0 = (tid & 15) * 2;
;     float m0 = 0.f, m1 = 0.f;
;     for (int k = 0; k < 32; ++k) { float av = As[(32 + i) * 65 + k]; m0 += av * Tf[k * 65 + j0]; m1 += av * Tf[k * 65 + j0 + 1]; }
;     Mt[i * 33 + j0] = m0; Mt[i * 33 + j0 + 1] = m1;
;   }
.LBB0_571:
	s_or_b64 exec, exec, s[0:1]
	v_lshlrev_b32_e32 v2, 1, v40
	v_ashrrev_i32_e32 v0, 4, v40
	v_and_b32_e32 v21, 30, v2
	v_mul_lo_u32 v28, v0, s75
	v_lshlrev_b32_e32 v30, 2, v21
	v_add_u32_e32 v29, v20, v28
	v_add_u32_e32 v31, v20, v30
	v_add_u32_e32 v2, 0x2080, v29
	s_waitcnt lgkmcnt(1)
	v_add_u32_e32 v4, 0x4400, v31
	s_waitcnt lgkmcnt(0)
	s_barrier
	v_mov_b32_e32 v240, s44
	v_lshrrev_b32_e32 v241, 8, v240
	v_add_u32_e32 v241, 1, v241
	v_min_u32_e32 v241, 7, v241
	v_and_b32_e32 v242, 63, v240
	v_lshlrev_b32_e32 v241, 12, v241
	v_lshl_or_b32 v241, v242, 6, v241
	v_mbcnt_lo_u32_b32 v243, -1, 0
	v_mbcnt_hi_u32_b32 v243, -1, v243
	v_or_b32_e32 v243, s33, v243
	v_lshrrev_b32_e32 v242, 3, v243
	v_and_b32_e32 v244, 7, v243
	v_add_u32_e32 v247, 2, v244
	v_lshrrev_b32_e32 v247, 3, v247
	v_sub_u32_e32 v247, 0, v247
	v_and_b32_e32 v245, 3, v242
	v_min_u32_e32 v245, 2, v245
	v_subrev_u32_e32 v245, 3, v245
	v_lshrrev_b32_e32 v246, 2, v242
	v_and_b32_e32 v246, 7, v246
	v_bfi_b32 v242, v247, v245, v242
	v_bfi_b32 v244, v247, v246, v244
	v_min_u32_e32 v244, 5, v244
	v_add_u32_e32 v241, v241, v242
	v_mul_u32_u24_e32 v241, 0x1c00, v241
	v_lshrrev_b32_e32 v245, 1, v244
	v_lshlrev_b32_e32 v245, 10, v245
	v_and_b32_e32 v244, 1, v244
	v_lshl_or_b32 v245, v244, 7, v245
	v_bfe_u32 v244, v240, 6, 2
	v_lshl_or_b32 v245, v244, 8, v245
	v_add_u32_e32 v241, v241, v245
	global_load_dword v247, v241, s[34:35]
	v_add_u32_e32 v8, 0x4504, v31
	v_add_u32_e32 v6, 0x2088, v29
	ds_read2_b32 v[2:3], v2 offset1:1
	ds_read2_b32 v[4:5], v4 offset1:1
	ds_read2_b32 v[6:7], v6 offset1:1
	ds_read2_b32 v[8:9], v8 offset1:1
	v_add_u32_e32 v12, 0x4608, v31
	v_add_u32_e32 v16, 0x470c, v31
	v_add_u32_e32 v10, 0x2090, v29
	v_add_u32_e32 v14, 0x4810, v31
	v_add_u32_e32 v26, 0x4914, v31
	v_add_u32_e32 v18, 0x2098, v29
	v_add_u32_e32 v22, 0x4a18, v31
	v_add_u32_e32 v24, 0x4b1c, v31
	s_waitcnt lgkmcnt(2)
	v_pk_fma_f32 v[4:5], v[2:3], v[4:5], 0 op_sel_hi:[0,1,0]
	ds_read2_b32 v[10:11], v10 offset1:1
	ds_read2_b32 v[12:13], v12 offset1:1
	ds_read2_b32 v[14:15], v14 offset1:1
	ds_read2_b32 v[16:17], v16 offset1:1
	ds_read2_b32 v[18:19], v18 offset1:1
	ds_read2_b32 v[22:23], v22 offset1:1
	ds_read2_b32 v[24:25], v24 offset1:1
	ds_read2_b32 v[26:27], v26 offset1:1
	s_waitcnt lgkmcnt(8)
	v_pk_fma_f32 v[2:3], v[2:3], v[8:9], v[4:5] op_sel:[1,0,0]
	v_add_u32_e32 v32, 0x20a0, v29
	s_waitcnt lgkmcnt(6)
	v_pk_fma_f32 v[2:3], v[6:7], v[12:13], v[2:3] op_sel_hi:[0,1,1]
	s_waitcnt lgkmcnt(4)
	v_pk_fma_f32 v[2:3], v[6:7], v[16:17], v[2:3] op_sel:[1,0,0]
	v_add_u32_e32 v33, 0x4c20, v31
	v_add_u32_e32 v36, 0x4d24, v31
	v_pk_fma_f32 v[2:3], v[10:11], v[14:15], v[2:3] op_sel_hi:[0,1,1]
	ds_read2_b32 v[4:5], v32 offset1:1
	ds_read2_b32 v[6:7], v33 offset1:1
	ds_read2_b32 v[8:9], v36 offset1:1
	s_waitcnt lgkmcnt(3)
	v_pk_fma_f32 v[2:3], v[10:11], v[26:27], v[2:3] op_sel:[1,0,0]
	v_add_u32_e32 v10, 0x20a8, v29
	v_pk_fma_f32 v[2:3], v[18:19], v[22:23], v[2:3] op_sel_hi:[0,1,1]
	v_pk_fma_f32 v[2:3], v[18:19], v[24:25], v[2:3] op_sel:[1,0,0]
	ds_read2_b32 v[10:11], v10 offset1:1
	s_waitcnt lgkmcnt(2)
	v_pk_fma_f32 v[2:3], v[4:5], v[6:7], v[2:3] op_sel_hi:[0,1,1]
	s_waitcnt lgkmcnt(1)
	v_pk_fma_f32 v[2:3], v[4:5], v[8:9], v[2:3] op_sel:[1,0,0]
	v_add_u32_e32 v4, 0x4e28, v31
	v_add_u32_e32 v12, 0x4f2c, v31
	v_add_u32_e32 v6, 0x20b0, v29
	v_add_u32_e32 v8, 0x5030, v31
	v_add_u32_e32 v22, 0x5134, v31
	v_add_u32_e32 v14, 0x20b8, v29
	v_add_u32_e32 v16, 0x5238, v31
	v_add_u32_e32 v18, 0x533c, v31
	ds_read2_b32 v[4:5], v4 offset1:1
	ds_read2_b32 v[6:7], v6 offset1:1
	ds_read2_b32 v[8:9], v8 offset1:1
	ds_read2_b32 v[12:13], v12 offset1:1
	ds_read2_b32 v[14:15], v14 offset1:1
	ds_read2_b32 v[16:17], v16 offset1:1
	ds_read2_b32 v[18:19], v18 offset1:1
	ds_read2_b32 v[22:23], v22 offset1:1
	s_waitcnt lgkmcnt(7)
	v_pk_fma_f32 v[2:3], v[10:11], v[4:5], v[2:3] op_sel_hi:[0,1,1]
	s_waitcnt lgkmcnt(4)
	v_pk_fma_f32 v[2:3], v[10:11], v[12:13], v[2:3] op_sel:[1,0,0]
	v_add_u32_e32 v24, 0x20c0, v29
	v_pk_fma_f32 v[2:3], v[6:7], v[8:9], v[2:3] op_sel_hi:[0,1,1]
	v_add_u32_e32 v25, 0x5440, v31
	s_waitcnt lgkmcnt(0)
	v_pk_fma_f32 v[2:3], v[6:7], v[22:23], v[2:3] op_sel:[1,0,0]
	v_add_u32_e32 v26, 0x5544, v31
	v_add_u32_e32 v27, 0x20c8, v29
	v_add_u32_e32 v32, 0x5648, v31
	v_add_u32_e32 v33, 0x574c, v31
	v_add_u32_e32 v36, 0x20d0, v29
	v_add_u32_e32 v37, 0x5850, v31
	v_pk_fma_f32 v[2:3], v[14:15], v[16:17], v[2:3] op_sel_hi:[0,1,1]
	ds_read2_b32 v[4:5], v24 offset1:1
	ds_read2_b32 v[6:7], v27 offset1:1
	ds_read2_b32 v[8:9], v25 offset1:1
	ds_read2_b32 v[10:11], v26 offset1:1
	ds_read2_b32 v[12:13], v36 offset1:1
	ds_read2_b32 v[16:17], v32 offset1:1
	ds_read2_b32 v[22:23], v37 offset1:1
	ds_read2_b32 v[24:25], v33 offset1:1
	v_pk_fma_f32 v[2:3], v[14:15], v[18:19], v[2:3] op_sel:[1,0,0]
	s_movk_i32 s0, 0x84
	s_waitcnt lgkmcnt(5)
	v_pk_fma_f32 v[2:3], v[4:5], v[8:9], v[2:3] op_sel_hi:[0,1,1]
	s_waitcnt lgkmcnt(4)
	v_pk_fma_f32 v[2:3], v[4:5], v[10:11], v[2:3] op_sel:[1,0,0]
	v_add_u32_e32 v4, 0x5954, v31
	s_waitcnt lgkmcnt(2)
	v_pk_fma_f32 v[2:3], v[6:7], v[16:17], v[2:3] op_sel_hi:[0,1,1]
	ds_read2_b32 v[4:5], v4 offset1:1
	s_waitcnt lgkmcnt(1)
	v_pk_fma_f32 v[2:3], v[6:7], v[24:25], v[2:3] op_sel:[1,0,0]
	v_add_u32_e32 v6, 0x20d8, v29
	v_add_u32_e32 v8, 0x5a58, v31
	v_add_u32_e32 v10, 0x5b5c, v31
	v_mul_lo_u32 v7, v0, s0
	s_mov_b32 s0, 0xa900
	v_add3_u32 v32, v31, v7, s0
	ds_read2_b32 v[6:7], v6 offset1:1
	ds_read2_b32 v[8:9], v8 offset1:1
	ds_read2_b32 v[10:11], v10 offset1:1
	v_pk_fma_f32 v[2:3], v[12:13], v[22:23], v[2:3] op_sel_hi:[0,1,1]
	v_add_u32_e32 v14, 0x20e0, v29
	s_waitcnt lgkmcnt(3)
; __device__ void dn_pre_item(const Params& p, int L, int idx) {
;     ...
;   { const int i = tid >> 4, j0 = (tid & 15) * 2;
;     float m0 = 0.f, m1 = 0.f;
;     for (int k = 0; k < 32; ++k) { float av = As[(32 + i) * 65 + k]; m0 += av * Tf[k * 65 + j0]; m1 += av * Tf[k * 65 + j0 + 1]; }
;     Mt[i * 33 + j0] = m0; Mt[i * 33 + j0 + 1] = m1;
;   }
;   __syncthreads();
;   { const int i = tid >> 4, j0 = (tid & 15) * 2;
;     float t0 = 0.f, t1 = 0.f;
;     for (int k = 0; k < 32; ++k) { float tv = Tf[(32 + i) * 65 + 32 + k]; t0 += tv * Mt[k * 33 + j0]; t1 += tv * Mt[k * 33 + j0 + 1]; }
;     Tb[(32 + i) * 72 + j0] = f2bf(-t0); Tb[(32 + i) * 72 + j0 + 1] = f2bf(-t1);
	v_pk_fma_f32 v[2:3], v[12:13], v[4:5], v[2:3] op_sel:[1,0,0]
	v_add_u32_e32 v15, 0x5c60, v31
	v_add_u32_e32 v17, 0x20e8, v29
	ds_read2_b32 v[4:5], v14 offset1:1
	ds_read2_b32 v[12:13], v15 offset1:1
	s_waitcnt lgkmcnt(3)
	v_pk_fma_f32 v[2:3], v[6:7], v[8:9], v[2:3] op_sel_hi:[0,1,1]
	v_add_u32_e32 v16, 0x5d64, v31
	s_waitcnt lgkmcnt(2)
	v_pk_fma_f32 v[2:3], v[6:7], v[10:11], v[2:3] op_sel:[1,0,0]
	ds_read2_b32 v[6:7], v17 offset1:1
	ds_read2_b32 v[8:9], v16 offset1:1
	v_add_u32_e32 v18, 0x5e68, v31
	v_add_u32_e32 v19, 0x5f6c, v31
	v_add_u32_e32 v22, 0x20f0, v29
	v_add_u32_e32 v23, 0x6070, v31
	v_add_u32_e32 v26, 0x6174, v31
	v_add_u32_e32 v24, 0x20f8, v29
	v_add_u32_e32 v25, 0x6278, v31
	v_add_u32_e32 v27, 0x637c, v31
	s_waitcnt lgkmcnt(2)
	v_pk_fma_f32 v[2:3], v[4:5], v[12:13], v[2:3] op_sel_hi:[0,1,1]
	ds_read2_b32 v[10:11], v22 offset1:1
	ds_read2_b32 v[12:13], v18 offset1:1
	ds_read2_b32 v[14:15], v23 offset1:1
	ds_read2_b32 v[16:17], v19 offset1:1
	ds_read2_b32 v[18:19], v24 offset1:1
	ds_read2_b32 v[22:23], v25 offset1:1
	ds_read2_b32 v[24:25], v27 offset1:1
	ds_read2_b32 v[26:27], v26 offset1:1
	s_waitcnt lgkmcnt(8)
	v_pk_fma_f32 v[2:3], v[4:5], v[8:9], v[2:3] op_sel:[1,0,0]
	v_add_u32_e32 v8, 0xa984, v31
	s_waitcnt lgkmcnt(6)
	v_pk_fma_f32 v[2:3], v[6:7], v[12:13], v[2:3] op_sel_hi:[0,1,1]
	s_waitcnt lgkmcnt(4)
	v_pk_fma_f32 v[2:3], v[6:7], v[16:17], v[2:3] op_sel:[1,0,0]
	v_add_u32_e32 v6, 0xa900, v31
	v_pk_fma_f32 v[2:3], v[10:11], v[14:15], v[2:3] op_sel_hi:[0,1,1]
	s_waitcnt lgkmcnt(0)
	v_pk_fma_f32 v[2:3], v[10:11], v[26:27], v[2:3] op_sel:[1,0,0]
	v_add_u32_e32 v4, 0x6508, v29
	v_pk_fma_f32 v[2:3], v[18:19], v[22:23], v[2:3] op_sel_hi:[0,1,1]
	v_pk_fma_f32 v[2:3], v[18:19], v[24:25], v[2:3] op_sel:[1,0,0]
	ds_write2_b32 v32, v2, v3 offset1:1
	v_add_u32_e32 v2, 0x6500, v29
	v_add_u32_e32 v10, 0xaa08, v31
	v_add_u32_e32 v14, 0xaa8c, v31
	v_add_u32_e32 v16, 0x6510, v29
	v_add_u32_e32 v12, 0xab10, v31
	s_waitcnt lgkmcnt(0)
	s_barrier
	ds_read2_b32 v[2:3], v2 offset1:1
	ds_read2_b32 v[4:5], v4 offset1:1
	ds_read2_b32 v[6:7], v6 offset1:1
	ds_read2_b32 v[8:9], v8 offset1:1
	ds_read2_b32 v[10:11], v10 offset1:1
	ds_read2_b32 v[12:13], v12 offset1:1
	ds_read2_b32 v[14:15], v14 offset1:1
	ds_read2_b32 v[16:17], v16 offset1:1
	s_waitcnt lgkmcnt(5)
	v_pk_fma_f32 v[6:7], v[2:3], v[6:7], 0 op_sel_hi:[0,1,0]
	s_waitcnt lgkmcnt(4)
	v_pk_fma_f32 v[2:3], v[2:3], v[8:9], v[6:7] op_sel:[1,0,0]
	v_add_u32_e32 v6, 0x6518, v29
	s_waitcnt lgkmcnt(3)
	v_pk_fma_f32 v[2:3], v[4:5], v[10:11], v[2:3] op_sel_hi:[0,1,1]
	s_waitcnt lgkmcnt(1)
	v_pk_fma_f32 v[2:3], v[4:5], v[14:15], v[2:3] op_sel:[1,0,0]
	v_add_u32_e32 v4, 0xab94, v31
	ds_read2_b32 v[4:5], v4 offset1:1
	v_add_u32_e32 v8, 0xac18, v31
	v_add_u32_e32 v10, 0xac9c, v31
	ds_read2_b32 v[6:7], v6 offset1:1
	ds_read2_b32 v[8:9], v8 offset1:1
	ds_read2_b32 v[10:11], v10 offset1:1
	s_waitcnt lgkmcnt(4)
	v_pk_fma_f32 v[2:3], v[16:17], v[12:13], v[2:3] op_sel_hi:[0,1,1]
	v_add_u32_e32 v12, 0x6520, v29
	v_add_u32_e32 v13, 0xad20, v31
	s_waitcnt lgkmcnt(3)
	v_pk_fma_f32 v[2:3], v[16:17], v[4:5], v[2:3] op_sel:[1,0,0]
	v_add_u32_e32 v15, 0x6528, v29
	ds_read2_b32 v[4:5], v12 offset1:1
	ds_read2_b32 v[12:13], v13 offset1:1
	s_waitcnt lgkmcnt(3)
	v_pk_fma_f32 v[2:3], v[6:7], v[8:9], v[2:3] op_sel_hi:[0,1,1]
	v_add_u32_e32 v14, 0xada4, v31
	s_waitcnt lgkmcnt(2)
	v_pk_fma_f32 v[2:3], v[6:7], v[10:11], v[2:3] op_sel:[1,0,0]
	ds_read2_b32 v[6:7], v15 offset1:1
	ds_read2_b32 v[8:9], v14 offset1:1
	v_add_u32_e32 v18, 0xae28, v31
	v_add_u32_e32 v19, 0xaeac, v31
	v_add_u32_e32 v22, 0x6530, v29
	v_add_u32_e32 v23, 0xaf30, v31
	v_add_u32_e32 v26, 0xafb4, v31
	v_add_u32_e32 v24, 0x6538, v29
	v_add_u32_e32 v25, 0xb038, v31
	v_add_u32_e32 v27, 0xb0bc, v31
	s_waitcnt lgkmcnt(2)
	v_pk_fma_f32 v[2:3], v[4:5], v[12:13], v[2:3] op_sel_hi:[0,1,1]
	ds_read2_b32 v[10:11], v22 offset1:1
	ds_read2_b32 v[12:13], v18 offset1:1
	ds_read2_b32 v[14:15], v23 offset1:1
	ds_read2_b32 v[16:17], v19 offset1:1
	ds_read2_b32 v[18:19], v24 offset1:1
	ds_read2_b32 v[22:23], v25 offset1:1
	ds_read2_b32 v[24:25], v27 offset1:1
	ds_read2_b32 v[26:27], v26 offset1:1
	s_waitcnt lgkmcnt(8)
	v_pk_fma_f32 v[2:3], v[4:5], v[8:9], v[2:3] op_sel:[1,0,0]
	v_add_u32_e32 v4, 0x6540, v29
	s_waitcnt lgkmcnt(6)
	v_pk_fma_f32 v[2:3], v[6:7], v[12:13], v[2:3] op_sel_hi:[0,1,1]
	s_waitcnt lgkmcnt(4)
	v_pk_fma_f32 v[2:3], v[6:7], v[16:17], v[2:3] op_sel:[1,0,0]
	v_add_u32_e32 v6, 0xb140, v31
	v_pk_fma_f32 v[2:3], v[10:11], v[14:15], v[2:3] op_sel_hi:[0,1,1]
	s_waitcnt lgkmcnt(0)
	v_pk_fma_f32 v[2:3], v[10:11], v[26:27], v[2:3] op_sel:[1,0,0]
	v_add_u32_e32 v10, 0xb1c4, v31
	v_pk_fma_f32 v[2:3], v[18:19], v[22:23], v[2:3] op_sel_hi:[0,1,1]
	v_pk_fma_f32 v[2:3], v[18:19], v[24:25], v[2:3] op_sel:[1,0,0]
	v_add_u32_e32 v8, 0x6548, v29
	v_add_u32_e32 v14, 0xb248, v31
	v_add_u32_e32 v18, 0xb2cc, v31
	v_add_u32_e32 v12, 0x6550, v29
	v_add_u32_e32 v16, 0xb350, v31
	ds_read2_b32 v[4:5], v4 offset1:1
	ds_read2_b32 v[6:7], v6 offset1:1
	ds_read2_b32 v[8:9], v8 offset1:1
	ds_read2_b32 v[10:11], v10 offset1:1
	ds_read2_b32 v[12:13], v12 offset1:1
	ds_read2_b32 v[14:15], v14 offset1:1
	ds_read2_b32 v[16:17], v16 offset1:1
	ds_read2_b32 v[18:19], v18 offset1:1
	s_waitcnt lgkmcnt(6)
	v_pk_fma_f32 v[2:3], v[4:5], v[6:7], v[2:3] op_sel_hi:[0,1,1]
	s_waitcnt lgkmcnt(4)
	v_pk_fma_f32 v[2:3], v[4:5], v[10:11], v[2:3] op_sel:[1,0,0]
	v_add_u32_e32 v22, 0xb3d4, v31
	s_waitcnt lgkmcnt(2)
; __device__ __forceinline__ unsigned pack2(float a, float b) { return (unsigned)f2bf(a) | ((unsigned)f2bf(b) << 16); }
; __device__ void dn_pre_item(const Params& p, int L, int idx) {
;     ...
;   { const int i = tid >> 4, j0 = (tid & 15) * 2;
;     float t0 = 0.f, t1 = 0.f;
;     for (int k = 0; k < 32; ++k) { float tv = Tf[(32 + i) * 65 + 32 + k]; t0 += tv * Mt[k * 33 + j0]; t1 += tv * Mt[k * 33 + j0 + 1]; }
;     Tb[(32 + i) * 72 + j0] = f2bf(-t0); Tb[(32 + i) * 72 + j0 + 1] = f2bf(-t1);
;     Tb[i * 72 + j0] = f2bf(Tf[i * 65 + j0]); Tb[i * 72 + j0 + 1] = f2bf(Tf[i * 65 + j0 + 1]);
;     Tb[i * 72 + 32 + j0] = 0; Tb[i * 72 + 32 + j0 + 1] = 0;
;     Tb[(32 + i) * 72 + 32 + j0] = f2bf(Tf[(32 + i) * 65 + 32 + j0]); Tb[(32 + i) * 72 + 32 + j0 + 1] = f2bf(Tf[(32 + i) * 65 + 32 + j0 + 1]);
;   }
;   __syncthreads();
;   { bf16x8 tf[4][2];
;     _Pragma("unroll") for (int rt = 0; rt < 4; ++rt) _Pragma("unroll") for (int k2 = 0; k2 < 2; ++k2)
;       tf[rt][k2] = *(const bf16x8*)(Tb + (rt * 16 + c16) * 72 + k2 * 32 + q4 * 8);
;     _Pragma("unroll") for (int cc = 0; cc < 2; ++cc) {
;       const int ct = wid * 2 + cc;
;       bf16x8 bf[2];
;       _Pragma("unroll") for (int k2 = 0; k2 < 2; ++k2) bf[k2] = *(const bf16x8*)(rhsT + (ct * 16 + c16) * 72 + k2 * 32 + q4 * 8);
;       _Pragma("unroll") for (int rt = 0; rt < 4; ++rt) {
;         f32x4 a = (f32x4){0.f, 0.f, 0.f, 0.f};
;         if (ct < 8) {
;           _Pragma("unroll") for (int k2 = 0; k2 < 2; ++k2) a = __builtin_amdgcn_mfma_f32_16x16x32_bf16(tf[rt][k2], bf[k2], a, 0, 0, 0);
;           u32x2 o2; o2[0] = pack2(a[0], a[1]); o2[1] = pack2(a[2], a[3]);
;           *(u32x2*)(dnp + 8192 + ((rt * 8 + ct) * 64 + lane) * 4) = o2;
;         } else {
;           _Pragma("unroll") for (int k2 = 0; k2 < 2; ++k2) a = __builtin_amdgcn_mfma_f32_16x16x32_bf16(bf[k2], tf[rt][k2], a, 0, 0, 0);
;           const int k0 = (ct - 8) * 16 + q4 * 4;
;           u32x2 o2; o2[0] = pack2(-a[0], -a[1]); o2[1] = pack2(-a[2], -a[3]);
;           *(u32x2*)(dnp + (rt * 4 + (k0 >> 5)) * 512 + ((k0 >> 3) & 3) * 128 + c16 * 8 + (k0 & 7)) = o2;
	v_pk_fma_f32 v[2:3], v[8:9], v[14:15], v[2:3] op_sel_hi:[0,1,1]
	v_add_u32_e32 v23, 0x6558, v29
	s_waitcnt lgkmcnt(0)
	v_pk_fma_f32 v[2:3], v[8:9], v[18:19], v[2:3] op_sel:[1,0,0]
	v_add_u32_e32 v24, 0xb458, v31
	v_add_u32_e32 v25, 0xb4dc, v31
	v_add_u32_e32 v26, 0x6560, v29
	v_add_u32_e32 v27, 0xb560, v31
	v_add_u32_e32 v32, 0xb5e4, v31
	v_add_u32_e32 v33, 0x6568, v29
	v_pk_fma_f32 v[2:3], v[12:13], v[16:17], v[2:3] op_sel_hi:[0,1,1]
	ds_read2_b32 v[4:5], v23 offset1:1
	ds_read2_b32 v[6:7], v24 offset1:1
	ds_read2_b32 v[8:9], v25 offset1:1
	ds_read2_b32 v[10:11], v22 offset1:1
	ds_read2_b32 v[14:15], v26 offset1:1
	ds_read2_b32 v[16:17], v33 offset1:1
	ds_read2_b32 v[18:19], v27 offset1:1
	ds_read2_b32 v[22:23], v32 offset1:1
	s_waitcnt lgkmcnt(4)
	v_pk_fma_f32 v[2:3], v[12:13], v[10:11], v[2:3] op_sel:[1,0,0]
	v_add_u32_e32 v36, 0xb668, v31
	v_pk_fma_f32 v[2:3], v[4:5], v[6:7], v[2:3] op_sel_hi:[0,1,1]
	v_pk_fma_f32 v[2:3], v[4:5], v[8:9], v[2:3] op_sel:[1,0,0]
	v_add_u32_e32 v6, 0xb6ec, v31
	s_waitcnt lgkmcnt(1)
	v_pk_fma_f32 v[2:3], v[14:15], v[18:19], v[2:3] op_sel_hi:[0,1,1]
	s_waitcnt lgkmcnt(0)
	v_pk_fma_f32 v[2:3], v[14:15], v[22:23], v[2:3] op_sel:[1,0,0]
	v_add_u32_e32 v8, 0x6570, v29
	v_add_u32_e32 v10, 0xb770, v31
	v_add_u32_e32 v22, 0xb7f4, v31
	v_add_u32_e32 v12, 0x6578, v29
	v_add_u32_e32 v14, 0xb878, v31
	v_add_u32_e32 v18, 0xb8fc, v31
	ds_read2_b32 v[4:5], v36 offset1:1
	ds_read2_b32 v[6:7], v6 offset1:1
	ds_read2_b32 v[8:9], v8 offset1:1
	ds_read2_b32 v[10:11], v10 offset1:1
	ds_read2_b32 v[12:13], v12 offset1:1
	ds_read2_b32 v[14:15], v14 offset1:1
	ds_read2_b32 v[18:19], v18 offset1:1
	ds_read2_b32 v[22:23], v22 offset1:1
	s_waitcnt lgkmcnt(7)
	v_pk_fma_f32 v[2:3], v[16:17], v[4:5], v[2:3] op_sel_hi:[0,1,1]
	s_waitcnt lgkmcnt(6)
	v_pk_fma_f32 v[2:3], v[16:17], v[6:7], v[2:3] op_sel:[1,0,0]
	s_movk_i32 s0, 0x4400
	s_waitcnt lgkmcnt(4)
	v_pk_fma_f32 v[2:3], v[8:9], v[10:11], v[2:3] op_sel_hi:[0,1,1]
	s_waitcnt lgkmcnt(0)
	v_pk_fma_f32 v[2:3], v[8:9], v[22:23], v[2:3] op_sel:[1,0,0]
	v_lshlrev_b32_e32 v4, 1, v21
	v_pk_fma_f32 v[2:3], v[12:13], v[14:15], v[2:3] op_sel_hi:[0,1,1]
	v_pk_fma_f32 v[2:3], v[12:13], v[18:19], v[2:3] op_sel:[1,0,0]
	v_mul_lo_u32 v0, v0, s55
	v_pk_add_f32 v[2:3], v[2:3], 0 neg_lo:[1,1] neg_hi:[1,1]
	v_add3_u32 v0, v20, v0, v4
	v_and_b32_sdwa v5, v3, v220 dst_sel:DWORD dst_unused:UNUSED_PAD src0_sel:WORD_1 src1_sel:DWORD
	v_and_b32_sdwa v6, v2, v220 dst_sel:DWORD dst_unused:UNUSED_PAD src0_sel:WORD_1 src1_sel:DWORD
	v_add3_u32 v2, v2, v6, s72
	v_add3_u32 v3, v3, v5, s72
	v_perm_b32 v6, v3, v2, s22
	v_add3_u32 v2, v29, v30, s0
	ds_read2_b32 v[2:3], v2 offset1:1
	s_movk_i32 s0, 0x6500
	v_add3_u32 v4, v28, v31, s0
	ds_read2_b32 v[4:5], v4 offset1:1
	v_cmp_lt_i32_e32 vcc, 3, v62
	s_waitcnt lgkmcnt(1)
	v_and_b32_sdwa v7, v3, v220 dst_sel:DWORD dst_unused:UNUSED_PAD src0_sel:WORD_1 src1_sel:DWORD
	v_and_b32_sdwa v8, v2, v220 dst_sel:DWORD dst_unused:UNUSED_PAD src0_sel:WORD_1 src1_sel:DWORD
	v_add3_u32 v2, v2, v8, s72
	v_add3_u32 v3, v3, v7, s72
	v_perm_b32 v2, v3, v2, s22
	v_add_u32_e32 v3, 0x8400, v0
	ds_write2_b32 v3, v2, v1 offset0:64 offset1:80
	s_waitcnt lgkmcnt(1)
	v_and_b32_sdwa v2, v5, v220 dst_sel:DWORD dst_unused:UNUSED_PAD src0_sel:WORD_1 src1_sel:DWORD
	v_and_b32_sdwa v3, v4, v220 dst_sel:DWORD dst_unused:UNUSED_PAD src0_sel:WORD_1 src1_sel:DWORD
	v_add3_u32 v3, v4, v3, s72
	v_add3_u32 v2, v5, v2, s72
	v_perm_b32 v2, v2, v3, s22
	v_add_u32_e32 v0, 0x9400, v0
	ds_write2_b32 v0, v6, v2 offset0:192 offset1:208
	v_and_b32_e32 v0, 48, v40
	v_mul_u32_u24_e32 v2, 0x90, v55
	v_add3_u32 v6, v20, v0, v2
	s_waitcnt lgkmcnt(0)
	s_barrier
	ds_read_b128 v[26:29], v6 offset:34048
	ds_read_b128 v[30:33], v6 offset:34112
	ds_read_b128 v[18:21], v6 offset:36352
	ds_read_b128 v[22:25], v6 offset:36416
	ds_read_b128 v[10:13], v6 offset:38656
	ds_read_b128 v[14:17], v6 offset:38720
	ds_read_b128 v[2:5], v6 offset:40960
	ds_read_b128 v[6:9], v6 offset:41024
	v_add_u32_e32 v54, v34, v0
	v_or_b32_e32 v0, v35, v55
	v_mad_u64_u32 v[38:39], s[0:1], v0, s55, v[54:55]
	ds_read_b128 v[34:37], v38
	ds_read_b128 v[38:41], v38 offset:64
	s_add_u32 s0, s46, 0x4000
	s_addc_u32 s1, s47, 0
	s_and_saveexec_b64 s[2:3], vcc
	s_xor_b64 s[12:13], exec, s[2:3]
	s_cbranch_execz .LBB0_573
	s_waitcnt lgkmcnt(1)
	v_mfma_f32_16x16x32_bf16 v[56:59], v[34:37], v[26:29], 0
	s_waitcnt lgkmcnt(0)
	v_mfma_f32_16x16x32_bf16 v[56:59], v[38:41], v[30:33], v[56:59]
	s_nop 7
	v_xor_b32_e32 v45, 0x80000000, v56
	v_xor_b32_e32 v48, 0x80000000, v58
	v_xor_b32_e32 v0, 0x80000000, v57
	v_xor_b32_e32 v44, 0x80000000, v59
	v_and_b32_sdwa v51, v48, v220 dst_sel:DWORD dst_unused:UNUSED_PAD src0_sel:WORD_1 src1_sel:DWORD
	v_and_b32_sdwa v52, v45, v220 dst_sel:DWORD dst_unused:UNUSED_PAD src0_sel:WORD_1 src1_sel:DWORD
	v_and_b32_sdwa v53, v44, v220 dst_sel:DWORD dst_unused:UNUSED_PAD src0_sel:WORD_1 src1_sel:DWORD
	v_add3_u32 v52, v45, v52, s72
	v_add3_u32 v45, v48, v51, s72
	v_and_b32_sdwa v48, v0, v220 dst_sel:DWORD dst_unused:UNUSED_PAD src0_sel:WORD_1 src1_sel:DWORD
	v_add3_u32 v44, v44, v53, s72
	v_add3_u32 v0, v0, v48, s72
	v_and_b32_e32 v44, 0xffff0000, v44
	v_and_b32_e32 v0, 0xffff0000, v0
	v_or_b32_sdwa v45, v44, v45 dst_sel:DWORD dst_unused:UNUSED_PAD src0_sel:DWORD src1_sel:WORD_1
	v_or_b32_sdwa v44, v0, v52 dst_sel:DWORD dst_unused:UNUSED_PAD src0_sel:DWORD src1_sel:WORD_1
